# ffnconv group loops: loop-header waits no longer drain the previous group's 8 stores (vmcnt(8) at header, full wait only on loop entry)
# speedup vs baseline: 1.0118x; 1.0038x over previous
.LBB0_1260:
	v_lshl_add_u64 v[26:27], v[24:25], 0, s[46:47]
	v_add_co_u32_e32 v28, vcc, 0x2000, v26
	v_lshl_add_u64 v[32:33], v[24:25], 0, s[44:45]
	s_nop 0
	v_addc_co_u32_e32 v29, vcc, 0, v27, vcc
	v_add_co_u32_e32 v34, vcc, 0x2000, v32
	v_lshl_add_u64 v[36:37], v[24:25], 0, s[48:49]
	s_nop 0
	v_addc_co_u32_e32 v35, vcc, 0, v33, vcc
	v_add_co_u32_e32 v42, vcc, 0x2000, v36
	s_waitcnt vmcnt(18)
	v_lshl_add_u64 v[46:47], v[24:25], 0, s[50:51]
	v_addc_co_u32_e32 v43, vcc, 0, v37, vcc
	v_add_co_u32_e32 v48, vcc, 0x2000, v46
	v_lshl_add_u64 v[52:53], v[24:25], 0, s[58:59]
	s_nop 0
	v_addc_co_u32_e32 v49, vcc, 0, v47, vcc
	global_load_dword v38, v[26:27], off nt
	global_load_dword v40, v[28:29], off offset:3072 nt
	global_load_dword v44, v[32:33], off nt
	global_load_dword v45, v[34:35], off offset:3072 nt
	s_nop 0
	global_load_dword v36, v[36:37], off nt
	s_nop 0
	global_load_dword v39, v[42:43], off offset:3072 nt
	global_load_dword v32, v[46:47], off nt
	global_load_dword v33, v[48:49], off offset:3072 nt
	v_lshl_add_u64 v[26:27], v[24:25], 0, s[52:53]
	v_add_co_u32_e32 v28, vcc, 0x2000, v26
	v_lshl_add_u64 v[34:35], v[24:25], 0, s[54:55]
	s_nop 0
	v_addc_co_u32_e32 v29, vcc, 0, v27, vcc
	v_add_co_u32_e32 v46, vcc, 0x2000, v34
	v_lshl_add_u64 v[48:49], v[24:25], 0, s[56:57]
	s_nop 0
	v_addc_co_u32_e32 v47, vcc, 0, v35, vcc
	v_add_co_u32_e32 v50, vcc, 0x2000, v48
	v_mov_b32_e32 v5, v3
	s_nop 0
	v_addc_co_u32_e32 v51, vcc, 0, v49, vcc
	v_add_co_u32_e32 v54, vcc, 0x2000, v52
	s_mov_b32 s4, 0
	s_nop 0
	v_addc_co_u32_e32 v55, vcc, 0, v53, vcc
	global_load_dword v43, v[26:27], off nt
	global_load_dword v42, v[28:29], off offset:3072 nt
	global_load_dword v37, v[34:35], off nt
	s_nop 0
	global_load_dword v34, v[46:47], off offset:3072 nt
	global_load_dword v35, v[48:49], off nt
	global_load_dword v41, v[50:51], off offset:3072 nt
	global_load_dword v2, v[52:53], off nt
	s_nop 0
	global_load_dword v47, v[54:55], off offset:3072 nt
	v_lshl_add_u64 v[26:27], v[24:25], 0, s[60:61]
	v_add_co_u32_e32 v28, vcc, 0x2000, v26
	v_lshl_add_u64 v[48:49], v[24:25], 0, s[62:63]
	s_nop 0
	v_addc_co_u32_e32 v29, vcc, 0, v27, vcc
	v_add_co_u32_e32 v50, vcc, 0x2000, v48
	v_lshl_add_u64 v[52:53], v[24:25], 0, s[64:65]
	s_nop 0
	v_addc_co_u32_e32 v51, vcc, 0, v49, vcc
	v_add_co_u32_e32 v54, vcc, 0x2000, v52
	s_mov_b64 s[8:9], s[92:93]
	s_nop 0
	v_addc_co_u32_e32 v55, vcc, 0, v53, vcc
	global_load_dword v57, v[26:27], off nt
	global_load_dword v61, v[28:29], off offset:3072 nt
	global_load_dword v65, v[48:49], off nt
	global_load_dword v66, v[50:51], off offset:3072 nt
	global_load_dword v63, v[54:55], off offset:3072 nt
	global_load_dword v67, v[52:53], off nt
	v_lshlrev_b64 v[26:27], 1, v[4:5]
	s_mov_b64 s[16:17], s[90:91]
	s_waitcnt vmcnt(0)
	s_branch .LBB0_1262

.LBB0_1262:
	s_waitcnt vmcnt(8)
	v_mov_b32_e32 v51, v47
	v_mov_b32_e32 v52, v61
	v_mov_b32_e32 v53, v66
	v_mov_b32_e32 v54, v63
	v_mov_b32_e32 v58, v2
	v_mov_b32_e32 v59, v57
	v_mov_b32_e32 v60, v65
	s_cmp_eq_u32 s4, 28
	v_mov_b32_e32 v62, v67
	s_cbranch_scc1 .LBB0_1261
	v_lshl_add_u64 v[28:29], s[8:9], 0, v[26:27]
	v_add_co_u32_e32 v46, vcc, 0x15933000, v28
	s_add_i32 s5, s18, s4
	s_nop 0
	v_addc_co_u32_e32 v47, vcc, 0, v29, vcc
	v_add_co_u32_e32 v48, vcc, 0x15936000, v28
	s_add_i32 s5, s5, 5
	s_nop 0
	v_addc_co_u32_e32 v49, vcc, 0, v29, vcc
	global_load_dword v5, v[46:47], off offset:2048 nt
	global_load_dword v7, v[48:49], off offset:1024 nt
	v_mov_b32_e32 v46, 0
	s_cmpk_gt_u32 s5, 0xdf
	v_mov_b32_e32 v49, 0
	v_mov_b32_e32 v50, 0
	s_cbranch_scc1 .LBB0_1265
	s_add_i32 s25, s19, s4
	s_add_i32 s25, s25, 37
	v_mad_i64_i32 v[48:49], s[28:29], s25, v94, v[24:25]
	v_add_co_u32_e32 v56, vcc, 0x2000, v48
	s_nop 1
	v_addc_co_u32_e32 v57, vcc, 0, v49, vcc
	global_load_dword v49, v[48:49], off nt
	s_nop 0
	global_load_dword v50, v[56:57], off offset:3072 nt

.LBB0_1298:
	v_ashrrev_i32_e32 v7, 31, v6
	v_lshlrev_b64 v[50:51], 1, v[6:7]
	s_mov_b32 s25, 0
	s_mov_b64 s[6:7], s[40:41]
	s_mov_b64 s[8:9], s[20:21]
	s_waitcnt vmcnt(0)
	s_branch .LBB0_1300

.LBB0_1300:
	s_waitcnt vmcnt(8)
	v_mov_b32_e32 v102, v97
	v_mov_b32_e32 v104, v113
	v_mov_b32_e32 v105, v115
	v_mov_b32_e32 v107, v130
	v_mov_b32_e32 v108, v136
	v_mov_b32_e32 v109, v139
	v_mov_b32_e32 v110, v141
	v_mov_b32_e32 v111, v140
	v_mov_b32_e32 v116, v2
	v_mov_b32_e32 v117, v112
	v_mov_b32_e32 v118, v99
	v_mov_b32_e32 v119, v127
	v_mov_b32_e32 v120, v126
	v_mov_b32_e32 v121, v137
	v_mov_b32_e32 v122, v138
	s_cmp_eq_u32 s25, 28
	v_mov_b32_e32 v125, v142
	s_cbranch_scc1 .LBB0_1299
	s_add_i32 s30, s22, s25
	s_add_i32 s30, s30, 5
	s_cmp_gt_u32 s30, 63
	s_cselect_b64 s[4:5], -1, 0
	s_cmp_lt_u32 s30, 64
	s_cselect_b64 s[28:29], -1, 0
	s_or_b64 vcc, s[66:67], s[4:5]
	v_mov_b32_e32 v7, 0
	s_and_b64 vcc, exec, vcc
	v_mov_b32_e32 v5, 0
	v_mov_b32_e32 v96, 0
	s_cbranch_vccnz .LBB0_1303
	s_add_i32 s31, s23, s25
	s_addk_i32 s31, 0xfc5
	v_mad_i64_i32 v[78:79], vcc, s31, v94, v[48:49]
	v_add_co_u32_e32 v84, vcc, 0x2000, v78
	s_nop 1
	v_addc_co_u32_e32 v85, vcc, 0, v79, vcc
	global_load_dword v5, v[78:79], off nt
	global_load_dword v96, v[84:85], off offset:3072 nt

.LBB0_2499:
	s_waitcnt vmcnt(8)
	v_mov_b32_e32 v51, v47
	v_mov_b32_e32 v52, v61
	v_mov_b32_e32 v53, v66
	v_mov_b32_e32 v54, v63
	v_mov_b32_e32 v58, v2
	v_mov_b32_e32 v59, v57
	v_mov_b32_e32 v60, v65
	s_cmp_eq_u32 s4, 28
	v_mov_b32_e32 v62, v67
	s_cbranch_scc1 .LBB0_2498
	v_lshl_add_u64 v[28:29], s[8:9], 0, v[26:27]
	v_add_co_u32_e32 v46, vcc, 0x15933000, v28
	s_add_i32 s5, s12, s4
	s_nop 0
	v_addc_co_u32_e32 v47, vcc, 0, v29, vcc
	v_add_co_u32_e32 v48, vcc, 0x15936000, v28
	s_add_i32 s5, s5, 5
	s_nop 0
	v_addc_co_u32_e32 v49, vcc, 0, v29, vcc
	global_load_dword v5, v[46:47], off offset:2048 nt
	global_load_dword v7, v[48:49], off offset:1024 nt
	v_mov_b32_e32 v46, 0
	s_cmpk_gt_u32 s5, 0xdf
	v_mov_b32_e32 v49, 0
	v_mov_b32_e32 v50, 0
	s_cbranch_scc1 .LBB0_2502
	s_add_i32 s23, s13, s4
	s_add_i32 s23, s23, 37
	v_mad_i64_i32 v[48:49], s[24:25], s23, v94, v[24:25]
	v_add_co_u32_e32 v56, vcc, 0x2000, v48
	s_nop 1
	v_addc_co_u32_e32 v57, vcc, 0, v49, vcc
	global_load_dword v49, v[48:49], off nt
	s_nop 0
	global_load_dword v50, v[56:57], off offset:3072 nt

.LBB0_2535:
	v_ashrrev_i32_e32 v7, 31, v6
	v_lshlrev_b64 v[50:51], 1, v[6:7]
	s_mov_b32 s23, 0
	s_mov_b64 s[6:7], s[40:41]
	s_mov_b64 s[8:9], s[20:21]
	s_waitcnt vmcnt(0)
	s_branch .LBB0_2537

.LBB0_2537:
	s_waitcnt vmcnt(8)
	v_mov_b32_e32 v102, v97
	v_mov_b32_e32 v104, v113
	v_mov_b32_e32 v105, v115
	v_mov_b32_e32 v107, v130
	v_mov_b32_e32 v108, v136
	v_mov_b32_e32 v109, v139
	v_mov_b32_e32 v110, v141
	v_mov_b32_e32 v111, v140
	v_mov_b32_e32 v116, v2
	v_mov_b32_e32 v117, v112
	v_mov_b32_e32 v118, v99
	v_mov_b32_e32 v119, v127
	v_mov_b32_e32 v120, v126
	v_mov_b32_e32 v121, v137
	v_mov_b32_e32 v122, v138
	s_cmp_eq_u32 s23, 28
	v_mov_b32_e32 v125, v142
	s_cbranch_scc1 .LBB0_2536
	s_add_i32 s24, s18, s23
	s_add_i32 s24, s24, 5
	s_cmp_gt_u32 s24, 63
	s_cselect_b64 s[4:5], -1, 0
	s_cmp_lt_u32 s24, 64
	s_cselect_b64 s[28:29], -1, 0
	s_or_b64 vcc, s[66:67], s[4:5]
	v_mov_b32_e32 v7, 0
	s_and_b64 vcc, exec, vcc
	v_mov_b32_e32 v5, 0
	v_mov_b32_e32 v96, 0
	s_cbranch_vccnz .LBB0_2540
	s_add_i32 s25, s19, s23
	s_addk_i32 s25, 0xfc5
	v_mad_i64_i32 v[78:79], vcc, s25, v94, v[48:49]
	v_add_co_u32_e32 v84, vcc, 0x2000, v78
	s_nop 1
	v_addc_co_u32_e32 v85, vcc, 0, v79, vcc
	global_load_dword v5, v[78:79], off nt
	global_load_dword v96, v[84:85], off offset:3072 nt
